# P0: replaced 19 serial tr_matrix loops with one balanced, pipelined transpose routine (32 loads in flight per tile, items round-robin over all waves)
# speedup vs baseline: 1.0263x; 1.0263x over previous
; #define LAS __attribute__((address_space(3)))
; __global__ void __launch_bounds__(512, 2) hymba_fwd(Args a) {
;     ...
;     bf16_t* WIN_T = (bf16_t*)(ws + WS_WIN); bf16_t* WOUT_T = (bf16_t*)(ws + WS_WOUT); bf16_t* WUP_T = (bf16_t*)(ws + WS_WUP); bf16_t* WDN_T = (bf16_t*)(ws + WS_WDN);
;     ...
;         LAS float* scr = (LAS float*)(lds + wid * 16384);
;         const float* w_in = a.in[6];
;         tr_matrix(w_in, 1024, 3096, 0, 512, WIN_T, 1024, 0, 0, a.in[2], 0.125f * 1.4426950408889634f, scr, gw, NGW, lane);
;         tr_matrix(w_in, 1024, 3096, 512, 384, WIN_T, 1024, 512, 0, a.in[2], 1.f, scr, gw, NGW, lane);
;         tr_matrix(w_in, 1024, 3096, 896, 128, WIN_T, 1024, ZVS, 0, a.in[2], 1.f, scr, gw, NGW, lane);
;         tr_matrix(w_in, 1024, 3096, 1024, 128, WIN_T, 1024, ZKW, 0, a.in[2], 1.f, scr, gw, NGW, lane);
;         tr_matrix(w_in, 1024, 3096, 1152, 128, WIN_T, 1024, ZVW, 0, a.in[2], 1.f, scr, gw, NGW, lane);
;         tr_matrix(w_in, 1024, 3096, 1280, 24, WIN_T, 1024, ZGT, 0, a.in[2], 1.f, scr, gw, NGW, lane);
;         tr_matrix(w_in, 1024, 3096, 1304, 1792, WIN_T, 1024, ZR, 0, a.in[2], 1.f, scr, gw, NGW, lane);
;         tr_matrix(a.in[27], 1024, 1024, 0, 1024, WOUT_T, 1024, 0, 0, nullptr, 1.f, scr, gw, NGW, lane);
;         tr_matrix(a.in[28], 1024, 4096, 0, 4096, WUP_T, 1024, 0, 0, a.in[4], 1.f, scr, gw, NGW, lane);
;         tr_matrix(a.in[29], 4096, 1024, 0, 1024, WDN_T, 4096, 0, 0, nullptr, 1.f, scr, gw, NGW, lane);
;         tr_matrix(a.in[30], 256, 1024, 0, 1024, WPLE_T, 256, 0, 0, nullptr, 1.f, scr, gw, NGW, lane);
;         tr_matrix(a.in[31], 1024, 1024, 0, 1024, WPG_T, 1024, 0, 0, nullptr, 1.f, scr, gw, NGW, lane);
;         tr_matrix(a.in[9], 2048, 128, 0, 128, CK1_T, 2048, 0, 0, nullptr, 1.f, scr, gw, NGW, lane);
;         tr_matrix(a.in[13], 2048, 128, 0, 128, CV1_T, 2048, 0, 0, nullptr, 1.f, scr, gw, NGW, lane);
;         tr_matrix(a.in[11], 128, 64, 0, 64, CK2_T, 256, 0, 0, nullptr, 1.f, scr, gw, NGW, lane);
;         tr_matrix(a.in[15], 128, 64, 0, 64, CV2_T, 256, 0, 0, nullptr, 1.f, scr, gw, NGW, lane);
;         tr_matrix(a.in[18], 64, 512, 0, 512, LORA_T, 256, 0, 0, nullptr, 1.f, scr, gw, NGW, lane);
;         tr_matrix(a.in[20], 64, 512, 0, 512, LORA_T, 256, 512, 64, nullptr, 1.f, scr, gw, NGW, lane);
;         tr_matrix(a.in[21], 128, 512, 0, 512, LORA_T, 256, 1024, 128, nullptr, 1.f, scr, gw, NGW, lane);
.LBB0_25:
	s_or_b64 exec, exec, s[0:1]
	s_lshr_b32 s28, s3, 6
	s_lshl_b32 s0, s2, 3
	v_writelane_b32 v247, s0, 38
	s_add_i32 s0, s28, s0
	s_lshl_b32 s94, s88, 3
	s_add_u32 s16, s86, 0x200000
	v_writelane_b32 v247, s0, 39
	s_addc_u32 s17, s87, 0
	v_and_b32_e32 v158, 63, v156
	v_writelane_b32 v247, s1, 40
	s_add_u32 s0, s86, 0x900000
	s_addc_u32 s1, s87, 0
	v_writelane_b32 v247, s0, 41
	s_nop 1
	v_writelane_b32 v247, s1, 42
	s_add_u32 s0, s86, 0xb00000
	s_addc_u32 s1, s87, 0
	v_writelane_b32 v247, s0, 43
	s_nop 1
	v_writelane_b32 v247, s1, 44
	s_add_u32 s0, s86, 0x1300000
	s_addc_u32 s1, s87, 0
	v_writelane_b32 v247, s0, 45
	s_nop 1
	v_writelane_b32 v247, s1, 46
	s_add_u32 s0, s86, 0x1b00000
	s_addc_u32 s1, s87, 0
	v_writelane_b32 v247, s0, 47
	s_nop 1
	v_writelane_b32 v247, s1, 48
	s_add_u32 s0, s86, 0x1c00000
	s_addc_u32 s1, s87, 0
	s_add_u32 s22, s86, 0x1e00000
	s_addc_u32 s23, s87, 0
	s_add_u32 s14, s86, 0x1f00000
	s_addc_u32 s15, s87, 0
	s_add_u32 s10, s86, 0x2000000
	s_addc_u32 s11, s87, 0
	s_add_u32 s8, s86, 0x2020000
	v_writelane_b32 v247, s0, 49
	s_addc_u32 s9, s87, 0
	s_nop 0
	v_writelane_b32 v247, s1, 50
	s_add_u32 s0, s86, 0x2100000
	s_addc_u32 s1, s87, 0
	s_add_u32 s24, s86, 0x2200000
	v_writelane_b32 v247, s0, 51
	s_addc_u32 s25, s87, 0
	s_add_u32 s96, s86, 0x9600000
	v_writelane_b32 v247, s1, 52
	s_addc_u32 s97, s87, 0
	v_readlane_b32 s4, v247, 3
	v_readlane_b32 s5, v247, 4
	s_cmp_lt_i32 s4, 1
	s_cselect_b64 s[0:1], -1, 0
	s_cmp_gt_i32 s5, 0
	s_cselect_b64 s[4:5], -1, 0
	s_and_b64 s[18:19], s[0:1], s[4:5]
	s_andn2_b64 vcc, exec, s[18:19]
	v_writelane_b32 v247, s88, 53
	s_nop 1
	v_writelane_b32 v247, s89, 54
	s_cbranch_vccnz .LBB0_291
	v_readlane_b32 s0, v247, 39
	s_lshl_b32 s1, s28, 14
	v_and_b32_e32 v78, 31, v158
	v_lshrrev_b32_e32 v79, 5, v158
	v_mul_u32_u24_e32 v120, 33, v79
	v_add_u32_e32 v120, v120, v78
	v_lshl_add_u32 v120, v120, 2, s1
	v_and_b32_e32 v121, 7, v158
	v_lshrrev_b32_e32 v122, 3, v158
	v_mul_u32_u24_e32 v123, 0x108, v121
	v_add_u32_e32 v123, v123, v122
	v_lshl_add_u32 v123, v123, 2, s1
	v_lshlrev_b32_e32 v125, 5, v121
.Ltr_item:
	s_cmpk_lt_u32 s0, 0x100
	s_cbranch_scc0 .Ltr_n0
	s_mov_b64 s[4:5], s[48:49]
	s_movk_i32 s6, 0x3060
	s_mov_b32 s7, s0
	s_mov_b32 s12, 0x1000
	s_movk_i32 s13, 0x10
	s_add_u32 s20, s86, 0x200000
	s_addc_u32 s21, s87, 0
	s_movk_i32 s26, 0x800
	s_mov_b64 s[32:33], s[40:41]
	s_mov_b32 s34, 0x3e38aa3b
	s_movk_i32 s35, 0x200
	s_branch .Ltr_body
.Ltr_n0:
	s_cmpk_lt_u32 s0, 0x1c0
	s_cbranch_scc0 .Ltr_n1
	s_add_u32 s4, s48, 0x800
	s_addc_u32 s5, s49, 0
	s_movk_i32 s6, 0x3060
	s_sub_u32 s7, s0, 0x100
	s_mov_b32 s12, 0x1556
	s_movk_i32 s13, 0xc
	s_add_u32 s20, s86, 0x300000
	s_addc_u32 s21, s87, 0
	s_movk_i32 s26, 0x800
	s_mov_b64 s[32:33], s[40:41]
	s_mov_b32 s34, 0x3f800000
	s_movk_i32 s35, 0x180
	s_branch .Ltr_body
.Ltr_n1:
	s_cmpk_lt_u32 s0, 0x200
	s_cbranch_scc0 .Ltr_n2
	s_add_u32 s4, s48, 0xe00
	s_addc_u32 s5, s49, 0
	s_movk_i32 s6, 0x3060
	s_sub_u32 s7, s0, 0x1c0
	s_mov_b32 s12, 0x4000
	s_movk_i32 s13, 0x4
	s_add_u32 s20, s86, 0x400000
	s_addc_u32 s21, s87, 0
	s_movk_i32 s26, 0x800
	s_mov_b64 s[32:33], s[40:41]
	s_mov_b32 s34, 0x3f800000
	s_movk_i32 s35, 0x80
	s_branch .Ltr_body
.Ltr_n2:
	s_cmpk_lt_u32 s0, 0x240
	s_cbranch_scc0 .Ltr_n3
	s_add_u32 s4, s48, 0x1000
	s_addc_u32 s5, s49, 0
	s_movk_i32 s6, 0x3060
	s_sub_u32 s7, s0, 0x200
	s_mov_b32 s12, 0x4000
	s_movk_i32 s13, 0x4
	s_add_u32 s20, s86, 0x3c0000
	s_addc_u32 s21, s87, 0
	s_movk_i32 s26, 0x800
	s_mov_b64 s[32:33], s[40:41]
	s_mov_b32 s34, 0x3f800000
	s_movk_i32 s35, 0x80
	s_branch .Ltr_body
.Ltr_n3:
	s_cmpk_lt_u32 s0, 0x280
	s_cbranch_scc0 .Ltr_n4
	s_add_u32 s4, s48, 0x1200
	s_addc_u32 s5, s49, 0
	s_movk_i32 s6, 0x3060
	s_sub_u32 s7, s0, 0x240
	s_mov_b32 s12, 0x4000
	s_movk_i32 s13, 0x4
	s_add_u32 s20, s86, 0x440000
	s_addc_u32 s21, s87, 0
	s_movk_i32 s26, 0x800
	s_mov_b64 s[32:33], s[40:41]
	s_mov_b32 s34, 0x3f800000
	s_movk_i32 s35, 0x80
	s_branch .Ltr_body
.Ltr_n4:
	s_cmpk_lt_u32 s0, 0x290
	s_cbranch_scc0 .Ltr_n5
	s_add_u32 s4, s48, 0x1400
	s_addc_u32 s5, s49, 0
	s_movk_i32 s6, 0x3060
	s_sub_u32 s7, s0, 0x280
	s_mov_b32 s12, 0x10000
	s_movk_i32 s13, 0x1
	s_add_u32 s20, s86, 0x800000
	s_addc_u32 s21, s87, 0
	s_movk_i32 s26, 0x800
	s_mov_b64 s[32:33], s[40:41]
	s_mov_b32 s34, 0x3f800000
	s_movk_i32 s35, 0x18
	s_branch .Ltr_body
.Ltr_n5:
	s_cmpk_lt_u32 s0, 0x610
	s_cbranch_scc0 .Ltr_n6
	s_add_u32 s4, s48, 0x1460
	s_addc_u32 s5, s49, 0
	s_movk_i32 s6, 0x3060
	s_sub_u32 s7, s0, 0x290
	s_mov_b32 s12, 0x493
	s_movk_i32 s13, 0x38
	s_add_u32 s20, s86, 0x480000
	s_addc_u32 s21, s87, 0
	s_movk_i32 s26, 0x800
	s_mov_b64 s[32:33], s[40:41]
	s_mov_b32 s34, 0x3f800000
	s_movk_i32 s35, 0x700
	s_branch .Ltr_body
.Ltr_n6:
	s_cmpk_lt_u32 s0, 0x810
	s_cbranch_scc0 .Ltr_n7
	v_readlane_b32 s4, v247, 27
	v_readlane_b32 s5, v247, 28
	s_movk_i32 s6, 0x1000
	s_sub_u32 s7, s0, 0x610
	s_mov_b32 s12, 0x800
	s_movk_i32 s13, 0x20
	s_add_u32 s20, s86, 0x900000
	s_addc_u32 s21, s87, 0
	s_movk_i32 s26, 0x800
	s_mov_b64 s[32:33], 0
	s_mov_b32 s34, 0x3f800000
	s_movk_i32 s35, 0x400
	s_branch .Ltr_body
.Ltr_n7:
	s_cmpk_lt_u32 s0, 0x1010
	s_cbranch_scc0 .Ltr_n8
	v_readlane_b32 s4, v247, 29
	v_readlane_b32 s5, v247, 30
	s_movk_i32 s6, 0x4000
	s_sub_u32 s7, s0, 0x810
	s_mov_b32 s12, 0x200
	s_movk_i32 s13, 0x80
	s_add_u32 s20, s86, 0xb00000
	s_addc_u32 s21, s87, 0
	s_movk_i32 s26, 0x800
	s_mov_b64 s[32:33], s[44:45]
	s_mov_b32 s34, 0x3f800000
	s_movk_i32 s35, 0x1000
	s_branch .Ltr_body
; #define LAS __attribute__((address_space(3)))
; __device__ __forceinline__ void tr_matrix(const float* W, int K, int ldn, int c0src, int ncols, bf16_t* WT, int ldk, int dst_row0, int dst_k0,
;                                           const float* rsc, float cs, LAS float* scr, int gw, int NGW, int lane) {
;     const int nkb = K / 64, nnb = (ncols + 31) / 32, nit = nkb * nnb;
;     for (int it = gw; it < nit; it += NGW) {
;         const int kb = it / nnb, nb = it % nnb, k0 = kb * 64, n0 = nb * 32, ncv = (ncols - n0) < 32 ? (ncols - n0) : 32;
; #pragma unroll 8
;         for (int i = 0; i < 32; ++i) { const int kk = 2 * i + (lane >> 5), col = lane & 31;
;             float val = 0.f;
;             if (col < ncv) { val = W[(size_t)(k0 + kk) * ldn + c0src + n0 + col]; if (rsc) val *= rsc[k0 + kk]; val *= cs; }
; __global__ void __launch_bounds__(512, 2) hymba_fwd(Args a) {
;     ...
;         tr_matrix(w_in, 1024, 3096, 1304, 1792, WIN_T, 1024, ZR, 0, a.in[2], 1.f, scr, gw, NGW, lane);
;         tr_matrix(a.in[27], 1024, 1024, 0, 1024, WOUT_T, 1024, 0, 0, nullptr, 1.f, scr, gw, NGW, lane);
;         tr_matrix(a.in[28], 1024, 4096, 0, 4096, WUP_T, 1024, 0, 0, a.in[4], 1.f, scr, gw, NGW, lane);
;         tr_matrix(a.in[29], 4096, 1024, 0, 1024, WDN_T, 4096, 0, 0, nullptr, 1.f, scr, gw, NGW, lane);
;         tr_matrix(a.in[30], 256, 1024, 0, 1024, WPLE_T, 256, 0, 0, nullptr, 1.f, scr, gw, NGW, lane);
;         tr_matrix(a.in[31], 1024, 1024, 0, 1024, WPG_T, 1024, 0, 0, nullptr, 1.f, scr, gw, NGW, lane);
;         tr_matrix(a.in[9], 2048, 128, 0, 128, CK1_T, 2048, 0, 0, nullptr, 1.f, scr, gw, NGW, lane);
;         tr_matrix(a.in[13], 2048, 128, 0, 128, CV1_T, 2048, 0, 0, nullptr, 1.f, scr, gw, NGW, lane);
;         tr_matrix(a.in[11], 128, 64, 0, 64, CK2_T, 256, 0, 0, nullptr, 1.f, scr, gw, NGW, lane);
;         tr_matrix(a.in[15], 128, 64, 0, 64, CV2_T, 256, 0, 0, nullptr, 1.f, scr, gw, NGW, lane);
;         tr_matrix(a.in[18], 64, 512, 0, 512, LORA_T, 256, 0, 0, nullptr, 1.f, scr, gw, NGW, lane);
;         tr_matrix(a.in[20], 64, 512, 0, 512, LORA_T, 256, 512, 64, nullptr, 1.f, scr, gw, NGW, lane);
;         tr_matrix(a.in[21], 128, 512, 0, 512, LORA_T, 256, 1024, 128, nullptr, 1.f, scr, gw, NGW, lane);
.Ltr_n8:
	s_cmpk_lt_u32 s0, 0x1810
	s_cbranch_scc0 .Ltr_n9
	v_readlane_b32 s4, v247, 31
	v_readlane_b32 s5, v247, 32
	s_movk_i32 s6, 0x1000
	s_sub_u32 s7, s0, 0x1010
	s_mov_b32 s12, 0x800
	s_movk_i32 s13, 0x20
	s_add_u32 s20, s86, 0x1300000
	s_addc_u32 s21, s87, 0
	s_movk_i32 s26, 0x2000
	s_mov_b64 s[32:33], 0
	s_mov_b32 s34, 0x3f800000
	s_movk_i32 s35, 0x400
	s_branch .Ltr_body
.Ltr_n9:
	s_cmpk_lt_u32 s0, 0x1890
	s_cbranch_scc0 .Ltr_n10
	v_readlane_b32 s4, v247, 33
	v_readlane_b32 s5, v247, 34
	s_movk_i32 s6, 0x1000
	s_sub_u32 s7, s0, 0x1810
	s_mov_b32 s12, 0x800
	s_movk_i32 s13, 0x20
	s_add_u32 s20, s86, 0x1b00000
	s_addc_u32 s21, s87, 0
	s_movk_i32 s26, 0x200
	s_mov_b64 s[32:33], 0
	s_mov_b32 s34, 0x3f800000
	s_movk_i32 s35, 0x400
	s_branch .Ltr_body
.Ltr_n10:
	s_cmpk_lt_u32 s0, 0x1a90
	s_cbranch_scc0 .Ltr_n11
	v_readlane_b32 s4, v247, 35
	v_readlane_b32 s5, v247, 36
	s_movk_i32 s6, 0x1000
	s_sub_u32 s7, s0, 0x1890
	s_mov_b32 s12, 0x800
	s_movk_i32 s13, 0x20
	s_add_u32 s20, s86, 0x1c00000
	s_addc_u32 s21, s87, 0
	s_movk_i32 s26, 0x800
	s_mov_b64 s[32:33], 0
	s_mov_b32 s34, 0x3f800000
	s_movk_i32 s35, 0x400
	s_branch .Ltr_body
.Ltr_n11:
	s_cmpk_lt_u32 s0, 0x1b10
	s_cbranch_scc0 .Ltr_n12
	s_mov_b64 s[4:5], s[54:55]
	s_movk_i32 s6, 0x200
	s_sub_u32 s7, s0, 0x1a90
	s_mov_b32 s12, 0x4000
	s_movk_i32 s13, 0x4
	s_add_u32 s20, s86, 0x1e00000
	s_addc_u32 s21, s87, 0
	s_movk_i32 s26, 0x1000
	s_mov_b64 s[32:33], 0
	s_mov_b32 s34, 0x3f800000
	s_movk_i32 s35, 0x80
	s_branch .Ltr_body
.Ltr_n12:
	s_cmpk_lt_u32 s0, 0x1b90
	s_cbranch_scc0 .Ltr_n13
	s_mov_b64 s[4:5], s[62:63]
	s_movk_i32 s6, 0x200
	s_sub_u32 s7, s0, 0x1b10
	s_mov_b32 s12, 0x4000
	s_movk_i32 s13, 0x4
	s_add_u32 s20, s86, 0x1f00000
	s_addc_u32 s21, s87, 0
	s_movk_i32 s26, 0x1000
	s_mov_b64 s[32:33], 0
	s_mov_b32 s34, 0x3f800000
	s_movk_i32 s35, 0x80
	s_branch .Ltr_body
.Ltr_n13:
	s_cmpk_lt_u32 s0, 0x1b94
	s_cbranch_scc0 .Ltr_n14
	s_mov_b64 s[4:5], s[58:59]
	s_movk_i32 s6, 0x100
	s_sub_u32 s7, s0, 0x1b90
	s_mov_b32 s12, 0x8000
	s_movk_i32 s13, 0x2
	s_add_u32 s20, s86, 0x2000000
	s_addc_u32 s21, s87, 0
	s_movk_i32 s26, 0x200
	s_mov_b64 s[32:33], 0
	s_mov_b32 s34, 0x3f800000
	s_movk_i32 s35, 0x40
	s_branch .Ltr_body
.Ltr_n14:
	s_cmpk_lt_u32 s0, 0x1b98
	s_cbranch_scc0 .Ltr_n15
	s_mov_b64 s[4:5], s[66:67]
	s_movk_i32 s6, 0x100
	s_sub_u32 s7, s0, 0x1b94
	s_mov_b32 s12, 0x8000
	s_movk_i32 s13, 0x2
	s_add_u32 s20, s86, 0x2020000
	s_addc_u32 s21, s87, 0
	s_movk_i32 s26, 0x200
	s_mov_b64 s[32:33], 0
	s_mov_b32 s34, 0x3f800000
	s_movk_i32 s35, 0x40
	s_branch .Ltr_body
.Ltr_n15:
	s_cmpk_lt_u32 s0, 0x1ba8
	s_cbranch_scc0 .Ltr_n16
	v_readlane_b32 s4, v247, 9
	v_readlane_b32 s5, v247, 10
	s_movk_i32 s6, 0x800
	s_sub_u32 s7, s0, 0x1b98
	s_mov_b32 s12, 0x1000
	s_movk_i32 s13, 0x10
	s_add_u32 s20, s86, 0x2100000
	s_addc_u32 s21, s87, 0
	s_movk_i32 s26, 0x200
	s_mov_b64 s[32:33], 0
	s_mov_b32 s34, 0x3f800000
	s_movk_i32 s35, 0x200
	s_branch .Ltr_body
.Ltr_n16:
	s_cmpk_lt_u32 s0, 0x1bb8
	s_cbranch_scc0 .Ltr_n17
	v_readlane_b32 s4, v247, 13
	v_readlane_b32 s5, v247, 14
	s_movk_i32 s6, 0x800
	s_sub_u32 s7, s0, 0x1ba8
	s_mov_b32 s12, 0x1000
	s_movk_i32 s13, 0x10
	s_add_u32 s20, s86, 0x2140080
	s_addc_u32 s21, s87, 0
	s_movk_i32 s26, 0x200
	s_mov_b64 s[32:33], 0
	s_mov_b32 s34, 0x3f800000
	s_movk_i32 s35, 0x200
	s_branch .Ltr_body
.Ltr_n17:
	v_readlane_b32 s4, v247, 15
	v_readlane_b32 s5, v247, 16
	s_movk_i32 s6, 0x800
	s_sub_u32 s7, s0, 0x1bb8
	s_mov_b32 s12, 0x1000
	s_movk_i32 s13, 0x10
	s_add_u32 s20, s86, 0x2180100
	s_addc_u32 s21, s87, 0
	s_movk_i32 s26, 0x200
	s_mov_b64 s[32:33], 0
	s_mov_b32 s34, 0x3f800000
	s_movk_i32 s35, 0x200
.Ltr_body:
	s_mul_i32 s68, s7, s12
	s_lshr_b32 s68, s68, 16
	s_mul_i32 s69, s68, s13
	s_sub_u32 s69, s7, s69
	s_lshl_b32 s70, s68, 6
	s_lshl_b32 s71, s69, 5
	s_cmp_eq_u64 s[32:33], 0
	s_cbranch_scc1 .Ltr_norsc
	s_lshl_b32 s76, s70, 2
	s_add_u32 s90, s32, s76
	s_addc_u32 s91, s33, 0
	global_load_dwordx4 v[112:115], v125, s[90:91]
	global_load_dwordx4 v[116:119], v125, s[90:91] offset:16
	s_branch .Ltr_rscdone
.Ltr_norsc:
	v_mov_b32_e32 v112, 1.0
	v_mov_b32_e32 v113, 1.0
	v_mov_b32_e32 v114, 1.0
	v_mov_b32_e32 v115, 1.0
	v_mov_b32_e32 v116, 1.0
	v_mov_b32_e32 v117, 1.0
	v_mov_b32_e32 v118, 1.0
	v_mov_b32_e32 v119, 1.0
; __device__ __forceinline__ void tr_matrix(const float* W, int K, int ldn, int c0src, int ncols, bf16_t* WT, int ldk, int dst_row0, int dst_k0,
;                                           const float* rsc, float cs, LAS float* scr, int gw, int NGW, int lane) {
;     ...
;     for (int it = gw; it < nit; it += NGW) {
;         const int kb = it / nnb, nb = it % nnb, k0 = kb * 64, n0 = nb * 32, ncv = (ncols - n0) < 32 ? (ncols - n0) : 32;
; #pragma unroll 8
;         for (int i = 0; i < 32; ++i) { const int kk = 2 * i + (lane >> 5), col = lane & 31;
;             float val = 0.f;
;             if (col < ncv) { val = W[(size_t)(k0 + kk) * ldn + c0src + n0 + col]; if (rsc) val *= rsc[k0 + kk]; val *= cs; }
;             scr[kk * 33 + col] = val; }
.Ltr_rscdone:
	s_mul_i32 s72, s70, s6
	s_lshl_b32 s76, s71, 2
	s_add_u32 s72, s72, s76
	s_add_u32 s72, s72, s4
	s_addc_u32 s73, s5, 0
	v_mul_lo_u32 v124, v79, s6
	v_lshl_add_u32 v124, v78, 2, v124
	s_lshl_b32 s77, s6, 1
	global_load_dword v80, v124, s[72:73]
	s_add_u32 s72, s72, s77
	s_addc_u32 s73, s73, 0
	global_load_dword v81, v124, s[72:73]
	s_add_u32 s72, s72, s77
	s_addc_u32 s73, s73, 0
	global_load_dword v82, v124, s[72:73]
	s_add_u32 s72, s72, s77
	s_addc_u32 s73, s73, 0
	global_load_dword v83, v124, s[72:73]
	s_add_u32 s72, s72, s77
	s_addc_u32 s73, s73, 0
	global_load_dword v84, v124, s[72:73]
	s_add_u32 s72, s72, s77
	s_addc_u32 s73, s73, 0
	global_load_dword v85, v124, s[72:73]
	s_add_u32 s72, s72, s77
	s_addc_u32 s73, s73, 0
	global_load_dword v86, v124, s[72:73]
	s_add_u32 s72, s72, s77
	s_addc_u32 s73, s73, 0
	global_load_dword v87, v124, s[72:73]
	s_add_u32 s72, s72, s77
	s_addc_u32 s73, s73, 0
	global_load_dword v88, v124, s[72:73]
	s_add_u32 s72, s72, s77
	s_addc_u32 s73, s73, 0
	global_load_dword v89, v124, s[72:73]
	s_add_u32 s72, s72, s77
	s_addc_u32 s73, s73, 0
	global_load_dword v90, v124, s[72:73]
	s_add_u32 s72, s72, s77
	s_addc_u32 s73, s73, 0
	global_load_dword v91, v124, s[72:73]
	s_add_u32 s72, s72, s77
	s_addc_u32 s73, s73, 0
	global_load_dword v92, v124, s[72:73]
	s_add_u32 s72, s72, s77
	s_addc_u32 s73, s73, 0
	global_load_dword v93, v124, s[72:73]
	s_add_u32 s72, s72, s77
	s_addc_u32 s73, s73, 0
	global_load_dword v94, v124, s[72:73]
	s_add_u32 s72, s72, s77
	s_addc_u32 s73, s73, 0
	global_load_dword v95, v124, s[72:73]
	s_add_u32 s72, s72, s77
	s_addc_u32 s73, s73, 0
	global_load_dword v96, v124, s[72:73]
	s_add_u32 s72, s72, s77
	s_addc_u32 s73, s73, 0
	global_load_dword v97, v124, s[72:73]
	s_add_u32 s72, s72, s77
	s_addc_u32 s73, s73, 0
	global_load_dword v98, v124, s[72:73]
	s_add_u32 s72, s72, s77
	s_addc_u32 s73, s73, 0
	global_load_dword v99, v124, s[72:73]
	s_add_u32 s72, s72, s77
	s_addc_u32 s73, s73, 0
	global_load_dword v100, v124, s[72:73]
	s_add_u32 s72, s72, s77
	s_addc_u32 s73, s73, 0
	global_load_dword v101, v124, s[72:73]
	s_add_u32 s72, s72, s77
	s_addc_u32 s73, s73, 0
	global_load_dword v102, v124, s[72:73]
	s_add_u32 s72, s72, s77
	s_addc_u32 s73, s73, 0
	global_load_dword v103, v124, s[72:73]
	s_add_u32 s72, s72, s77
	s_addc_u32 s73, s73, 0
	global_load_dword v104, v124, s[72:73]
	s_add_u32 s72, s72, s77
	s_addc_u32 s73, s73, 0
	global_load_dword v105, v124, s[72:73]
	s_add_u32 s72, s72, s77
	s_addc_u32 s73, s73, 0
	global_load_dword v106, v124, s[72:73]
	s_add_u32 s72, s72, s77
	s_addc_u32 s73, s73, 0
	global_load_dword v107, v124, s[72:73]
	s_add_u32 s72, s72, s77
	s_addc_u32 s73, s73, 0
	global_load_dword v108, v124, s[72:73]
	s_add_u32 s72, s72, s77
	s_addc_u32 s73, s73, 0
	global_load_dword v109, v124, s[72:73]
	s_add_u32 s72, s72, s77
	s_addc_u32 s73, s73, 0
	global_load_dword v110, v124, s[72:73]
	s_add_u32 s72, s72, s77
	s_addc_u32 s73, s73, 0
	global_load_dword v111, v124, s[72:73]
	v_add_u32_e32 v126, s71, v122
	v_mul_lo_u32 v126, v126, s26
	s_lshl_b32 s76, s70, 1
	v_lshl_add_u32 v127, v121, 4, s76
	v_add_u32_e32 v126, v126, v127
	s_lshl_b32 s78, s26, 3
	s_sub_u32 s79, s35, s71
	s_waitcnt vmcnt(31)
	ds_write_b32 v120, v80
	s_waitcnt vmcnt(30)
	ds_write_b32 v120, v81 offset:264
	s_waitcnt vmcnt(29)
	ds_write_b32 v120, v82 offset:528
	s_waitcnt vmcnt(28)
	ds_write_b32 v120, v83 offset:792
	s_waitcnt vmcnt(27)
	ds_write_b32 v120, v84 offset:1056
	s_waitcnt vmcnt(26)
	ds_write_b32 v120, v85 offset:1320
	s_waitcnt vmcnt(25)
	ds_write_b32 v120, v86 offset:1584
	s_waitcnt vmcnt(24)
	ds_write_b32 v120, v87 offset:1848
	s_waitcnt vmcnt(23)
	ds_write_b32 v120, v88 offset:2112
	s_waitcnt vmcnt(22)
	ds_write_b32 v120, v89 offset:2376
	s_waitcnt vmcnt(21)
	ds_write_b32 v120, v90 offset:2640
	s_waitcnt vmcnt(20)
	ds_write_b32 v120, v91 offset:2904
	s_waitcnt vmcnt(19)
	ds_write_b32 v120, v92 offset:3168
	s_waitcnt vmcnt(18)
	ds_write_b32 v120, v93 offset:3432
	s_waitcnt vmcnt(17)
	ds_write_b32 v120, v94 offset:3696
	s_waitcnt vmcnt(16)
	ds_write_b32 v120, v95 offset:3960
	s_waitcnt vmcnt(15)
	ds_write_b32 v120, v96 offset:4224
	s_waitcnt vmcnt(14)
	ds_write_b32 v120, v97 offset:4488
	s_waitcnt vmcnt(13)
	ds_write_b32 v120, v98 offset:4752
	s_waitcnt vmcnt(12)
	ds_write_b32 v120, v99 offset:5016
	s_waitcnt vmcnt(11)
	ds_write_b32 v120, v100 offset:5280
	s_waitcnt vmcnt(10)
	ds_write_b32 v120, v101 offset:5544
	s_waitcnt vmcnt(9)
	ds_write_b32 v120, v102 offset:5808
	s_waitcnt vmcnt(8)
	ds_write_b32 v120, v103 offset:6072
	s_waitcnt vmcnt(7)
	ds_write_b32 v120, v104 offset:6336
	s_waitcnt vmcnt(6)
	ds_write_b32 v120, v105 offset:6600
	s_waitcnt vmcnt(5)
; #define LAS __attribute__((address_space(3)))
; __device__ __forceinline__ unsigned pk2(float lo, float hi) { f32x2 v = {lo, hi}; bf16x2_t b = __builtin_convertvector(v, bf16x2_t); return __builtin_bit_cast(unsigned, b); }
; #define LDS_WAIT() asm volatile("s_waitcnt lgkmcnt(0)" ::: "memory")
; __device__ __forceinline__ void tr_matrix(const float* W, int K, int ldn, int c0src, int ncols, bf16_t* WT, int ldk, int dst_row0, int dst_k0,
;                                           const float* rsc, float cs, LAS float* scr, int gw, int NGW, int lane) {
;     ...
;         LDS_WAIT(); asm volatile("" ::: "memory");
;         const int c = lane & 7;
; #pragma unroll
;         for (int j = 0; j < 4; ++j) { const int n = (lane >> 3) + 8 * j; const LAS float* s = scr + (8 * c) * 33 + n;
;             if (n < ncv) {
;                 u32x4 o; o.x = pk2(s[0 * 33], s[1 * 33]); o.y = pk2(s[2 * 33], s[3 * 33]); o.z = pk2(s[4 * 33], s[5 * 33]); o.w = pk2(s[6 * 33], s[7 * 33]);
;                 *(u32x4*)(WT + (size_t)(dst_row0 + n0 + n) * ldk + dst_k0 + k0 + 8 * c) = o; } }
;         LDS_WAIT(); asm volatile("" ::: "memory");
;     }
	ds_write_b32 v120, v106 offset:6864
	s_waitcnt vmcnt(4)
	ds_write_b32 v120, v107 offset:7128
	s_waitcnt vmcnt(3)
	ds_write_b32 v120, v108 offset:7392
	s_waitcnt vmcnt(2)
	ds_write_b32 v120, v109 offset:7656
	s_waitcnt vmcnt(1)
	ds_write_b32 v120, v110 offset:7920
	s_waitcnt vmcnt(0)
	ds_write_b32 v120, v111 offset:8184
	s_waitcnt lgkmcnt(0)
	ds_read2_b32 v[80:81], v123 offset1:33
	ds_read2_b32 v[82:83], v123 offset0:66 offset1:99
	ds_read2_b32 v[84:85], v123 offset0:132 offset1:165
	ds_read2_b32 v[86:87], v123 offset0:198 offset1:231
	ds_read2_b32 v[88:89], v123 offset0:8 offset1:41
	ds_read2_b32 v[90:91], v123 offset0:74 offset1:107
	ds_read2_b32 v[92:93], v123 offset0:140 offset1:173
	ds_read2_b32 v[94:95], v123 offset0:206 offset1:239
	ds_read2_b32 v[96:97], v123 offset0:16 offset1:49
	ds_read2_b32 v[98:99], v123 offset0:82 offset1:115
	ds_read2_b32 v[100:101], v123 offset0:148 offset1:181
	ds_read2_b32 v[102:103], v123 offset0:214 offset1:247
	ds_read2_b32 v[104:105], v123 offset0:24 offset1:57
	ds_read2_b32 v[106:107], v123 offset0:90 offset1:123
	ds_read2_b32 v[108:109], v123 offset0:156 offset1:189
	ds_read2_b32 v[110:111], v123 offset0:222 offset1:255
	s_waitcnt lgkmcnt(12)
	v_mul_f32_e32 v80, v80, v112
	v_mul_f32_e32 v81, v81, v113
	v_mul_f32_e32 v82, v82, v114
	v_mul_f32_e32 v83, v83, v115
	v_mul_f32_e32 v84, v84, v116
	v_mul_f32_e32 v85, v85, v117
	v_mul_f32_e32 v86, v86, v118
	v_mul_f32_e32 v87, v87, v119
	v_mul_f32_e32 v80, s34, v80
	v_mul_f32_e32 v81, s34, v81
	v_mul_f32_e32 v82, s34, v82
	v_mul_f32_e32 v83, s34, v83
	v_mul_f32_e32 v84, s34, v84
	v_mul_f32_e32 v85, s34, v85
	v_mul_f32_e32 v86, s34, v86
	v_mul_f32_e32 v87, s34, v87
	v_cvt_pk_bf16_f32 v128, v80, v81
	v_cvt_pk_bf16_f32 v129, v82, v83
	v_cvt_pk_bf16_f32 v130, v84, v85
	v_cvt_pk_bf16_f32 v131, v86, v87
	v_cmp_gt_u32_e32 vcc, s79, v122
	s_and_saveexec_b64 s[92:93], vcc
	global_store_dwordx4 v126, v[128:131], s[20:21]
	s_mov_b64 exec, s[92:93]
	v_add_u32_e32 v126, s78, v126
	s_waitcnt lgkmcnt(8)
	v_mul_f32_e32 v88, v88, v112
	v_mul_f32_e32 v89, v89, v113
	v_mul_f32_e32 v90, v90, v114
	v_mul_f32_e32 v91, v91, v115
	v_mul_f32_e32 v92, v92, v116
	v_mul_f32_e32 v93, v93, v117
	v_mul_f32_e32 v94, v94, v118
	v_mul_f32_e32 v95, v95, v119
	v_mul_f32_e32 v88, s34, v88
	v_mul_f32_e32 v89, s34, v89
	v_mul_f32_e32 v90, s34, v90
	v_mul_f32_e32 v91, s34, v91
	v_mul_f32_e32 v92, s34, v92
	v_mul_f32_e32 v93, s34, v93
	v_mul_f32_e32 v94, s34, v94
	v_mul_f32_e32 v95, s34, v95
	v_cvt_pk_bf16_f32 v132, v88, v89
	v_cvt_pk_bf16_f32 v133, v90, v91
	v_cvt_pk_bf16_f32 v134, v92, v93
	v_cvt_pk_bf16_f32 v135, v94, v95
	v_add_u32_e32 v136, 8, v122
	v_cmp_gt_u32_e32 vcc, s79, v136
	s_and_saveexec_b64 s[92:93], vcc
	global_store_dwordx4 v126, v[132:135], s[20:21]
	s_mov_b64 exec, s[92:93]
	v_add_u32_e32 v126, s78, v126
	s_waitcnt lgkmcnt(4)
	v_mul_f32_e32 v96, v96, v112
	v_mul_f32_e32 v97, v97, v113
	v_mul_f32_e32 v98, v98, v114
	v_mul_f32_e32 v99, v99, v115
	v_mul_f32_e32 v100, v100, v116
	v_mul_f32_e32 v101, v101, v117
	v_mul_f32_e32 v102, v102, v118
	v_mul_f32_e32 v103, v103, v119
	v_mul_f32_e32 v96, s34, v96
	v_mul_f32_e32 v97, s34, v97
	v_mul_f32_e32 v98, s34, v98
	v_mul_f32_e32 v99, s34, v99
	v_mul_f32_e32 v100, s34, v100
	v_mul_f32_e32 v101, s34, v101
	v_mul_f32_e32 v102, s34, v102
	v_mul_f32_e32 v103, s34, v103
	v_cvt_pk_bf16_f32 v128, v96, v97
	v_cvt_pk_bf16_f32 v129, v98, v99
	v_cvt_pk_bf16_f32 v130, v100, v101
	v_cvt_pk_bf16_f32 v131, v102, v103
	v_add_u32_e32 v136, 16, v122
	v_cmp_gt_u32_e32 vcc, s79, v136
	s_and_saveexec_b64 s[92:93], vcc
	global_store_dwordx4 v126, v[128:131], s[20:21]
	s_mov_b64 exec, s[92:93]
	v_add_u32_e32 v126, s78, v126
	s_waitcnt lgkmcnt(0)
	v_mul_f32_e32 v104, v104, v112
	v_mul_f32_e32 v105, v105, v113
	v_mul_f32_e32 v106, v106, v114
	v_mul_f32_e32 v107, v107, v115
	v_mul_f32_e32 v108, v108, v116
	v_mul_f32_e32 v109, v109, v117
	v_mul_f32_e32 v110, v110, v118
	v_mul_f32_e32 v111, v111, v119
	v_mul_f32_e32 v104, s34, v104
	v_mul_f32_e32 v105, s34, v105
	v_mul_f32_e32 v106, s34, v106
	v_mul_f32_e32 v107, s34, v107
	v_mul_f32_e32 v108, s34, v108
	v_mul_f32_e32 v109, s34, v109
	v_mul_f32_e32 v110, s34, v110
	v_mul_f32_e32 v111, s34, v111
	v_cvt_pk_bf16_f32 v132, v104, v105
	v_cvt_pk_bf16_f32 v133, v106, v107
	v_cvt_pk_bf16_f32 v134, v108, v109
	v_cvt_pk_bf16_f32 v135, v110, v111
	v_add_u32_e32 v136, 24, v122
	v_cmp_gt_u32_e32 vcc, s79, v136
	s_and_saveexec_b64 s[92:93], vcc
	global_store_dwordx4 v126, v[132:135], s[20:21]
	s_mov_b64 exec, s[92:93]
	s_addk_i32 s0, 0x800
	s_cmpk_lt_u32 s0, 0x1bd8
	s_cbranch_scc1 .Ltr_item
	v_readlane_b32 s0, v247, 39
	v_and_b32_e32 v0, 31, v156
	v_lshrrev_b32_e32 v32, 3, v158
	s_cmpk_lt_i32 s0, 0x100
	s_cselect_b64 s[20:21], -1, 0
